# static s_setprio 1 for waves 0-3 (other half) at token-mixer phase entry
# speedup vs baseline: 1.0008x; 1.0008x over previous
; __global__ void __launch_bounds__(NT, 2) trunk_fwd(Args args) {
;     ...
;         if (IN(pb + 1)) for (int rep = 0; rep < (even ? REP_ATTN : 1); ++rep) {
.LBB0_522:
	s_andn2_b64 vcc, exec, s[0:1]
	s_cbranch_vccnz .LBB0_754
	v_readfirstlane_b32 s0, v232
	s_nop 0
	s_lshr_b32 s0, s0, 6
	s_cmp_ge_u32 s0, 4
	s_cbranch_scc1 .Lprio_mix_done
	s_setprio 1
